# in-proj GEMM K-loop restructured from 8 phases of 16 MFMA to 4 phases of 32 MFMA per barrier pair (same LDS stages and LDS-DMA; stage reuse schedule and counted vmcnt(6)/(4) re-derived, one extra prol
# speedup vs baseline: 1.0175x; 1.0175x over previous
.LBB0_379:
	v_lshrrev_b32_e32 v2, 1, v0
	v_and_b32_e32 v2, 24, v2
	s_sext_i32_i8 s80, s0
	s_and_b64 s[36:37], s[8:9], exec
	s_movk_i32 s0, 0x1a40
	v_and_b32_e32 v1, 15, v0
	v_lshlrev_b32_e32 v3, 1, v2
	v_lshlrev_b32_e32 v0, 2, v0
	s_cselect_b32 s59, s0, 0x2040
	v_lshl_or_b32 v136, s4, 6, v1
	v_lshl_or_b32 v1, v1, 6, v3
	s_lshl_b32 s0, s4, 13
	v_and_b32_e32 v0, 32, v0
	v_bitop3_b32 v139, v1, s0, v0 bitop3:0xde
	s_lshl_b32 s0, s1, 5
	s_and_b32 s4, s0, 0x60
	s_lshl_b32 s0, s4, 7
	v_readlane_b32 s7, v253, 40
	v_bitop3_b32 v146, v1, s0, v0 bitop3:0xde
	s_add_u32 s0, s12, s7
	v_mov_b32_e32 v133, v145
	s_addc_u32 s1, s13, 0
	s_add_i32 s62, s45, 0x18000
	v_mov_b32_e32 v129, v145
	v_lshl_add_u64 v[0:1], s[0:1], 0, v[132:133]
	s_mov_b32 m0, s62
	s_add_i32 s63, s45, 0x1a000
	s_waitcnt vmcnt(4)
	s_barrier
	global_load_lds_dwordx4 v[0:1], off
	v_lshl_add_u64 v[0:1], s[0:1], 0, v[128:129]
	s_add_u32 s0, s14, s7
	v_mov_b32_e32 v135, v145
	s_mov_b32 m0, s63
	s_addc_u32 s1, s15, 0
	s_add_i32 s76, s45, 0x8000
	v_mov_b32_e32 v131, v145
	global_load_lds_dwordx4 v[0:1], off
	v_lshl_add_u64 v[0:1], s[0:1], 0, v[134:135]
	s_mov_b32 m0, s76
	s_add_i32 s77, s45, 0xa000
	global_load_lds_dwordx4 v[0:1], off
	v_lshl_add_u64 v[0:1], s[0:1], 0, v[130:131]
	s_add_u32 s0, s5, s7
	s_mov_b32 m0, s77
	s_addc_u32 s1, s6, 0
	s_add_i32 s78, s45, 0x1c000
	global_load_lds_dwordx4 v[0:1], off
	v_lshl_add_u64 v[0:1], s[0:1], 0, v[132:133]
	s_mov_b32 m0, s78
	s_add_i32 s79, s45, 0x1e000
	global_load_lds_dwordx4 v[0:1], off
	v_lshl_add_u64 v[0:1], s[0:1], 0, v[128:129]
	s_mov_b32 m0, s79
	v_ashrrev_i32_e32 v137, 31, v136
	global_load_lds_dwordx4 v[0:1], off
	v_or_b32_e32 v0, 16, v136
	v_ashrrev_i32_e32 v1, 31, v0
	v_lshlrev_b64 v[140:141], 9, v[136:137]
	v_lshlrev_b64 v[142:143], 9, v[0:1]
	v_or_b32_e32 v0, 32, v136
	s_mov_b64 s[0:1], 0x10000
	v_ashrrev_i32_e32 v1, 31, v0
	v_lshl_add_u64 v[152:153], v[140:141], 0, s[0:1]
	s_mov_b64 s[0:1], 0x12000
	s_waitcnt vmcnt(6)
	v_lshlrev_b64 v[148:149], 9, v[0:1]
	v_or_b32_e32 v0, 48, v136
	v_lshl_add_u64 v[154:155], v[140:141], 0, s[0:1]
	s_mov_b64 s[0:1], 0x14000
	v_ashrrev_i32_e32 v1, 31, v0
	v_lshl_add_u64 v[156:157], v[140:141], 0, s[0:1]
	s_mov_b64 s[0:1], 0x16000
	s_mov_b32 s60, 0
	v_or_b32_e32 v138, s4, v2
	v_lshlrev_b64 v[150:151], 9, v[0:1]
	v_lshl_add_u64 v[158:159], v[140:141], 0, s[0:1]
	s_add_i32 s81, s45, 0xc000
	s_add_i32 s82, s45, 0xe000
	s_barrier
	s_barrier
	s_branch .LBB0_381

.LBB0_388:
	s_cmpk_eq_i32 s85, 0xf80
	s_cselect_b32 s39, s5, s15
	s_cselect_b32 s38, s4, s14
	s_cselect_b32 s88, s7, s13
	s_cselect_b32 s89, s6, s12
	s_add_i32 s36, s86, 3
	s_cmpk_eq_i32 s85, 0xf80
	s_cselect_b32 s36, 1, s36
	s_add_i32 s87, s86, 2
	s_cmpk_eq_i32 s85, 0xf80
	s_cselect_b32 s37, 0, s87
	s_add_i32 s37, s37, s64
	s_add_i32 s36, s36, s64
	s_add_i32 s40, s66, s85
	s_lshl_b32 s37, s37, 7
	s_lshl_b32 s36, s36, 7
	s_and_b32 s91, s40, 0xf80
	s_and_b32 s92, s37, 0xf80
	s_and_b32 s90, s36, 0xf80
	s_add_u32 s40, s89, s92
	s_addc_u32 s41, s88, 0
	s_add_u32 s38, s38, s92
	s_addc_u32 s39, s39, 0
	s_add_u32 s36, s12, s91
	s_addc_u32 s37, s13, 0
	s_add_u32 s36, s36, 0x84000
	s_addc_u32 s37, s37, 0
	s_add_u32 s92, s14, s91
	s_addc_u32 s93, s15, 0
	v_add_u32_e32 v137, 0x10000, v146
	ds_read_b128 v[160:163], v137
	ds_read_b128 v[164:167], v137 offset:1024
	ds_read_b128 v[168:171], v137 offset:2048
	ds_read_b128 v[188:191], v137 offset:3072
	v_add_u32_e32 v144, 0x14000, v146
	ds_read_b128 v[224:227], v144
	ds_read_b128 v[228:231], v144 offset:1024
	ds_read_b128 v[232:235], v144 offset:2048
	ds_read_b128 v[236:239], v144 offset:3072
	ds_read_b128 v[192:195], v139
	ds_read_b128 v[196:199], v139 offset:1024
	ds_read_b128 v[200:203], v139 offset:2048
	ds_read_b128 v[204:207], v139 offset:3072
	v_lshl_add_u64 v[172:173], s[92:93], 0, v[134:135]
	s_mov_b32 m0, s76
	s_nop 0
	global_load_lds_dwordx4 v[172:173], off
	v_lshl_add_u64 v[172:173], s[92:93], 0, v[130:131]
	s_mov_b32 m0, s77
	s_nop 0
	global_load_lds_dwordx4 v[172:173], off
	v_lshl_add_u64 v[172:173], s[36:37], 0, v[132:133]
	s_mov_b32 m0, s78
	s_nop 0
	global_load_lds_dwordx4 v[172:173], off
	v_lshl_add_u64 v[172:173], s[36:37], 0, v[128:129]
	s_mov_b32 m0, s79
	s_nop 0
	global_load_lds_dwordx4 v[172:173], off
	s_waitcnt lgkmcnt(11)
	ds_read_b128 v[208:211], v139 offset:4096
	ds_read_b128 v[212:215], v139 offset:5120
	ds_read_b128 v[216:219], v139 offset:6144
	ds_read_b128 v[220:223], v139 offset:7168
	s_waitcnt vmcnt(6)
	s_waitcnt lgkmcnt(8)
	s_barrier
	s_waitcnt lgkmcnt(0)
	s_setprio 1
	v_mfma_f32_16x16x32_bf16 v[124:127], v[160:163], v[192:195], v[124:127]
	v_mfma_f32_16x16x32_bf16 v[120:123], v[168:171], v[192:195], v[120:123]
	v_mfma_f32_16x16x32_bf16 v[112:115], v[160:163], v[200:203], v[112:115]
	v_mfma_f32_16x16x32_bf16 v[108:111], v[168:171], v[200:203], v[108:111]
	v_mfma_f32_16x16x32_bf16 v[104:107], v[160:163], v[208:211], v[104:107]
	v_mfma_f32_16x16x32_bf16 v[96:99], v[168:171], v[208:211], v[96:99]
	v_mfma_f32_16x16x32_bf16 v[88:91], v[160:163], v[216:219], v[88:91]
	v_mfma_f32_16x16x32_bf16 v[80:83], v[168:171], v[216:219], v[80:83]
	v_mfma_f32_16x16x32_bf16 v[124:127], v[164:167], v[196:199], v[124:127]
	v_mfma_f32_16x16x32_bf16 v[120:123], v[188:191], v[196:199], v[120:123]
	v_mfma_f32_16x16x32_bf16 v[112:115], v[164:167], v[204:207], v[112:115]
	v_mfma_f32_16x16x32_bf16 v[108:111], v[188:191], v[204:207], v[108:111]
	v_mfma_f32_16x16x32_bf16 v[104:107], v[164:167], v[212:215], v[104:107]
	v_mfma_f32_16x16x32_bf16 v[96:99], v[188:191], v[212:215], v[96:99]
	v_mfma_f32_16x16x32_bf16 v[88:91], v[164:167], v[220:223], v[88:91]
	v_mfma_f32_16x16x32_bf16 v[80:83], v[188:191], v[220:223], v[80:83]
	v_mfma_f32_16x16x32_bf16 v[116:119], v[224:227], v[192:195], v[116:119]
	v_mfma_f32_16x16x32_bf16 v[100:103], v[232:235], v[192:195], v[100:103]
	v_mfma_f32_16x16x32_bf16 v[92:95], v[224:227], v[200:203], v[92:95]
	v_mfma_f32_16x16x32_bf16 v[84:87], v[232:235], v[200:203], v[84:87]
	v_mfma_f32_16x16x32_bf16 v[76:79], v[224:227], v[208:211], v[76:79]
	v_mfma_f32_16x16x32_bf16 v[72:75], v[232:235], v[208:211], v[72:75]
	v_mfma_f32_16x16x32_bf16 v[68:71], v[224:227], v[216:219], v[68:71]
	v_mfma_f32_16x16x32_bf16 v[64:67], v[232:235], v[216:219], v[64:67]
	v_mfma_f32_16x16x32_bf16 v[116:119], v[228:231], v[196:199], v[116:119]
	v_mfma_f32_16x16x32_bf16 v[100:103], v[236:239], v[196:199], v[100:103]
	v_mfma_f32_16x16x32_bf16 v[92:95], v[228:231], v[204:207], v[92:95]
	v_mfma_f32_16x16x32_bf16 v[84:87], v[236:239], v[204:207], v[84:87]
	v_mfma_f32_16x16x32_bf16 v[76:79], v[228:231], v[212:215], v[76:79]
	v_mfma_f32_16x16x32_bf16 v[72:75], v[236:239], v[212:215], v[72:75]
	v_mfma_f32_16x16x32_bf16 v[68:71], v[228:231], v[220:223], v[68:71]
	v_mfma_f32_16x16x32_bf16 v[64:67], v[236:239], v[220:223], v[64:67]
	s_setprio 0
	s_barrier
	ds_read_b128 v[192:195], v139 offset:16384
	ds_read_b128 v[196:199], v139 offset:17408
	ds_read_b128 v[200:203], v139 offset:18432
	ds_read_b128 v[204:207], v139 offset:19456
	ds_read_b128 v[208:211], v139 offset:20480
	ds_read_b128 v[212:215], v139 offset:21504
	ds_read_b128 v[216:219], v139 offset:22528
	ds_read_b128 v[220:223], v139 offset:23552
	s_add_u32 s92, s92, 0x84000
	s_addc_u32 s93, s93, 0
	v_lshl_add_u64 v[172:173], s[92:93], 0, v[134:135]
	s_mov_b32 m0, s81
	s_nop 0
	global_load_lds_dwordx4 v[172:173], off
	v_lshl_add_u64 v[172:173], s[92:93], 0, v[130:131]
	s_mov_b32 m0, s82
	s_nop 0
	global_load_lds_dwordx4 v[172:173], off
	v_lshl_add_u64 v[172:173], s[40:41], 0, v[132:133]
	s_mov_b32 m0, s52
	s_nop 0
	global_load_lds_dwordx4 v[172:173], off
	v_lshl_add_u64 v[172:173], s[40:41], 0, v[128:129]
	s_mov_b32 m0, s53
	s_nop 0
	global_load_lds_dwordx4 v[172:173], off
	s_waitcnt vmcnt(4)
	s_barrier
	s_waitcnt lgkmcnt(0)
	s_setprio 1
	v_mfma_f32_16x16x32_bf16 v[60:63], v[160:163], v[192:195], v[60:63]
	v_mfma_f32_16x16x32_bf16 v[56:59], v[168:171], v[192:195], v[56:59]
	v_mfma_f32_16x16x32_bf16 v[52:55], v[160:163], v[200:203], v[52:55]
	v_mfma_f32_16x16x32_bf16 v[48:51], v[168:171], v[200:203], v[48:51]
	v_mfma_f32_16x16x32_bf16 v[40:43], v[160:163], v[208:211], v[40:43]
	v_mfma_f32_16x16x32_bf16 v[36:39], v[168:171], v[208:211], v[36:39]
	v_mfma_f32_16x16x32_bf16 v[24:27], v[160:163], v[216:219], v[24:27]
	v_mfma_f32_16x16x32_bf16 v[20:23], v[168:171], v[216:219], v[20:23]
	v_mfma_f32_16x16x32_bf16 v[60:63], v[164:167], v[196:199], v[60:63]
	v_mfma_f32_16x16x32_bf16 v[56:59], v[188:191], v[196:199], v[56:59]
	v_mfma_f32_16x16x32_bf16 v[52:55], v[164:167], v[204:207], v[52:55]
	v_mfma_f32_16x16x32_bf16 v[48:51], v[188:191], v[204:207], v[48:51]
	v_mfma_f32_16x16x32_bf16 v[40:43], v[164:167], v[212:215], v[40:43]
	v_mfma_f32_16x16x32_bf16 v[36:39], v[188:191], v[212:215], v[36:39]
	v_mfma_f32_16x16x32_bf16 v[24:27], v[164:167], v[220:223], v[24:27]
	v_mfma_f32_16x16x32_bf16 v[20:23], v[188:191], v[220:223], v[20:23]
	v_mfma_f32_16x16x32_bf16 v[44:47], v[224:227], v[192:195], v[44:47]
	v_mfma_f32_16x16x32_bf16 v[32:35], v[232:235], v[192:195], v[32:35]
	v_mfma_f32_16x16x32_bf16 v[28:31], v[224:227], v[200:203], v[28:31]
	v_mfma_f32_16x16x32_bf16 v[16:19], v[232:235], v[200:203], v[16:19]
	v_mfma_f32_16x16x32_bf16 v[12:15], v[224:227], v[208:211], v[12:15]
	v_mfma_f32_16x16x32_bf16 v[8:11], v[232:235], v[208:211], v[8:11]
	v_mfma_f32_16x16x32_bf16 v[4:7], v[224:227], v[216:219], v[4:7]
	v_mfma_f32_16x16x32_bf16 v[0:3], v[232:235], v[216:219], v[0:3]
	v_mfma_f32_16x16x32_bf16 v[44:47], v[228:231], v[196:199], v[44:47]
	v_mfma_f32_16x16x32_bf16 v[32:35], v[236:239], v[196:199], v[32:35]
	v_mfma_f32_16x16x32_bf16 v[28:31], v[228:231], v[204:207], v[28:31]
	v_mfma_f32_16x16x32_bf16 v[16:19], v[236:239], v[204:207], v[16:19]
	v_mfma_f32_16x16x32_bf16 v[12:15], v[228:231], v[212:215], v[12:15]
	v_mfma_f32_16x16x32_bf16 v[8:11], v[236:239], v[212:215], v[8:11]
	v_mfma_f32_16x16x32_bf16 v[4:7], v[228:231], v[220:223], v[4:7]
	v_mfma_f32_16x16x32_bf16 v[0:3], v[236:239], v[220:223], v[0:3]
	s_setprio 0
	s_barrier
	v_add_u32_e32 v137, 0x18000, v146
	ds_read_b128 v[160:163], v137
	ds_read_b128 v[164:167], v137 offset:1024
	ds_read_b128 v[168:171], v137 offset:2048
	ds_read_b128 v[188:191], v137 offset:3072
	v_add_u32_e32 v144, 0x1c000, v146
	ds_read_b128 v[224:227], v144
	ds_read_b128 v[228:231], v144 offset:1024
	ds_read_b128 v[232:235], v144 offset:2048
	ds_read_b128 v[236:239], v144 offset:3072
	ds_read_b128 v[192:195], v139 offset:32768
	ds_read_b128 v[196:199], v139 offset:33792
	ds_read_b128 v[200:203], v139 offset:34816
	ds_read_b128 v[204:207], v139 offset:35840
	v_lshl_add_u64 v[172:173], s[38:39], 0, v[134:135]
	s_mov_b32 m0, s45
	s_nop 0
	global_load_lds_dwordx4 v[172:173], off
	v_lshl_add_u64 v[172:173], s[38:39], 0, v[130:131]
	s_mov_b32 m0, s54
	s_nop 0
	global_load_lds_dwordx4 v[172:173], off
	s_add_u32 s40, s40, 0x84000
	s_addc_u32 s41, s41, 0
	v_lshl_add_u64 v[172:173], s[40:41], 0, v[132:133]
	s_mov_b32 m0, s55
	s_nop 0
	global_load_lds_dwordx4 v[172:173], off
	v_lshl_add_u64 v[172:173], s[40:41], 0, v[128:129]
	s_mov_b32 m0, s56
	s_nop 0
	global_load_lds_dwordx4 v[172:173], off
	s_waitcnt lgkmcnt(11)
	ds_read_b128 v[208:211], v139 offset:36864
	ds_read_b128 v[212:215], v139 offset:37888
	ds_read_b128 v[216:219], v139 offset:38912
	ds_read_b128 v[220:223], v139 offset:39936
	s_waitcnt vmcnt(6)
	s_waitcnt lgkmcnt(8)
	s_barrier
	s_waitcnt lgkmcnt(0)
	s_setprio 1
	v_mfma_f32_16x16x32_bf16 v[124:127], v[160:163], v[192:195], v[124:127]
	v_mfma_f32_16x16x32_bf16 v[120:123], v[168:171], v[192:195], v[120:123]
	v_mfma_f32_16x16x32_bf16 v[112:115], v[160:163], v[200:203], v[112:115]
	v_mfma_f32_16x16x32_bf16 v[108:111], v[168:171], v[200:203], v[108:111]
	v_mfma_f32_16x16x32_bf16 v[104:107], v[160:163], v[208:211], v[104:107]
	v_mfma_f32_16x16x32_bf16 v[96:99], v[168:171], v[208:211], v[96:99]
	v_mfma_f32_16x16x32_bf16 v[88:91], v[160:163], v[216:219], v[88:91]
	v_mfma_f32_16x16x32_bf16 v[80:83], v[168:171], v[216:219], v[80:83]
	v_mfma_f32_16x16x32_bf16 v[124:127], v[164:167], v[196:199], v[124:127]
	v_mfma_f32_16x16x32_bf16 v[120:123], v[188:191], v[196:199], v[120:123]
	v_mfma_f32_16x16x32_bf16 v[112:115], v[164:167], v[204:207], v[112:115]
	v_mfma_f32_16x16x32_bf16 v[108:111], v[188:191], v[204:207], v[108:111]
	v_mfma_f32_16x16x32_bf16 v[104:107], v[164:167], v[212:215], v[104:107]
	v_mfma_f32_16x16x32_bf16 v[96:99], v[188:191], v[212:215], v[96:99]
	v_mfma_f32_16x16x32_bf16 v[88:91], v[164:167], v[220:223], v[88:91]
	v_mfma_f32_16x16x32_bf16 v[80:83], v[188:191], v[220:223], v[80:83]
	v_mfma_f32_16x16x32_bf16 v[116:119], v[224:227], v[192:195], v[116:119]
	v_mfma_f32_16x16x32_bf16 v[100:103], v[232:235], v[192:195], v[100:103]
	v_mfma_f32_16x16x32_bf16 v[92:95], v[224:227], v[200:203], v[92:95]
	v_mfma_f32_16x16x32_bf16 v[84:87], v[232:235], v[200:203], v[84:87]
	v_mfma_f32_16x16x32_bf16 v[76:79], v[224:227], v[208:211], v[76:79]
	v_mfma_f32_16x16x32_bf16 v[72:75], v[232:235], v[208:211], v[72:75]
	v_mfma_f32_16x16x32_bf16 v[68:71], v[224:227], v[216:219], v[68:71]
	v_mfma_f32_16x16x32_bf16 v[64:67], v[232:235], v[216:219], v[64:67]
	v_mfma_f32_16x16x32_bf16 v[116:119], v[228:231], v[196:199], v[116:119]
	v_mfma_f32_16x16x32_bf16 v[100:103], v[236:239], v[196:199], v[100:103]
	v_mfma_f32_16x16x32_bf16 v[92:95], v[228:231], v[204:207], v[92:95]
	v_mfma_f32_16x16x32_bf16 v[84:87], v[236:239], v[204:207], v[84:87]
	v_mfma_f32_16x16x32_bf16 v[76:79], v[228:231], v[212:215], v[76:79]
	v_mfma_f32_16x16x32_bf16 v[72:75], v[236:239], v[212:215], v[72:75]
	v_mfma_f32_16x16x32_bf16 v[68:71], v[228:231], v[220:223], v[68:71]
	v_mfma_f32_16x16x32_bf16 v[64:67], v[236:239], v[220:223], v[64:67]
	s_setprio 0
	s_barrier
	ds_read_b128 v[192:195], v139 offset:49152
	ds_read_b128 v[196:199], v139 offset:50176
	ds_read_b128 v[200:203], v139 offset:51200
	ds_read_b128 v[204:207], v139 offset:52224
	ds_read_b128 v[208:211], v139 offset:53248
	ds_read_b128 v[212:215], v139 offset:54272
	ds_read_b128 v[216:219], v139 offset:55296
	ds_read_b128 v[220:223], v139 offset:56320
	s_add_u32 s38, s38, 0x84000
	s_addc_u32 s39, s39, 0
	v_lshl_add_u64 v[172:173], s[38:39], 0, v[134:135]
	s_mov_b32 m0, s57
	s_nop 0
	global_load_lds_dwordx4 v[172:173], off
	v_lshl_add_u64 v[172:173], s[38:39], 0, v[130:131]
	s_mov_b32 m0, s58
	s_nop 0
	global_load_lds_dwordx4 v[172:173], off
	s_add_u32 s36, s89, s90
	s_addc_u32 s37, s88, 0
	v_lshl_add_u64 v[172:173], s[36:37], 0, v[132:133]
	s_mov_b32 m0, s62
	s_nop 0
	global_load_lds_dwordx4 v[172:173], off
	v_lshl_add_u64 v[172:173], s[36:37], 0, v[128:129]
	s_mov_b32 m0, s63
	s_nop 0
	global_load_lds_dwordx4 v[172:173], off
	s_waitcnt vmcnt(4)
	s_barrier
	s_waitcnt lgkmcnt(0)
	s_setprio 1
	v_mfma_f32_16x16x32_bf16 v[60:63], v[160:163], v[192:195], v[60:63]
	v_mfma_f32_16x16x32_bf16 v[56:59], v[168:171], v[192:195], v[56:59]
	v_mfma_f32_16x16x32_bf16 v[52:55], v[160:163], v[200:203], v[52:55]
	v_mfma_f32_16x16x32_bf16 v[48:51], v[168:171], v[200:203], v[48:51]
	v_mfma_f32_16x16x32_bf16 v[40:43], v[160:163], v[208:211], v[40:43]
	v_mfma_f32_16x16x32_bf16 v[36:39], v[168:171], v[208:211], v[36:39]
	v_mfma_f32_16x16x32_bf16 v[24:27], v[160:163], v[216:219], v[24:27]
	v_mfma_f32_16x16x32_bf16 v[20:23], v[168:171], v[216:219], v[20:23]
	v_mfma_f32_16x16x32_bf16 v[60:63], v[164:167], v[196:199], v[60:63]
	v_mfma_f32_16x16x32_bf16 v[56:59], v[188:191], v[196:199], v[56:59]
	v_mfma_f32_16x16x32_bf16 v[52:55], v[164:167], v[204:207], v[52:55]
	v_mfma_f32_16x16x32_bf16 v[48:51], v[188:191], v[204:207], v[48:51]
	v_mfma_f32_16x16x32_bf16 v[40:43], v[164:167], v[212:215], v[40:43]
	v_mfma_f32_16x16x32_bf16 v[36:39], v[188:191], v[212:215], v[36:39]
	v_mfma_f32_16x16x32_bf16 v[24:27], v[164:167], v[220:223], v[24:27]
	v_mfma_f32_16x16x32_bf16 v[20:23], v[188:191], v[220:223], v[20:23]
	v_mfma_f32_16x16x32_bf16 v[44:47], v[224:227], v[192:195], v[44:47]
	v_mfma_f32_16x16x32_bf16 v[32:35], v[232:235], v[192:195], v[32:35]
	v_mfma_f32_16x16x32_bf16 v[28:31], v[224:227], v[200:203], v[28:31]
	v_mfma_f32_16x16x32_bf16 v[16:19], v[232:235], v[200:203], v[16:19]
	v_mfma_f32_16x16x32_bf16 v[12:15], v[224:227], v[208:211], v[12:15]
	v_mfma_f32_16x16x32_bf16 v[8:11], v[232:235], v[208:211], v[8:11]
	v_mfma_f32_16x16x32_bf16 v[4:7], v[224:227], v[216:219], v[4:7]
	v_mfma_f32_16x16x32_bf16 v[0:3], v[232:235], v[216:219], v[0:3]
	v_mfma_f32_16x16x32_bf16 v[44:47], v[228:231], v[196:199], v[44:47]
	v_mfma_f32_16x16x32_bf16 v[32:35], v[236:239], v[196:199], v[32:35]
	v_mfma_f32_16x16x32_bf16 v[28:31], v[228:231], v[204:207], v[28:31]
	v_mfma_f32_16x16x32_bf16 v[16:19], v[236:239], v[204:207], v[16:19]
	v_mfma_f32_16x16x32_bf16 v[12:15], v[228:231], v[212:215], v[12:15]
	v_mfma_f32_16x16x32_bf16 v[8:11], v[236:239], v[212:215], v[8:11]
	v_mfma_f32_16x16x32_bf16 v[4:7], v[228:231], v[220:223], v[4:7]
	v_mfma_f32_16x16x32_bf16 v[0:3], v[236:239], v[220:223], v[0:3]
	s_setprio 0
	s_addk_i32 s85, 0x100
	s_cmp_gt_u32 s86, 29
	s_mov_b32 s86, s87
	s_barrier
	s_cbranch_scc0 .LBB0_388
	s_lshl_b32 s36, s80, 8
	v_lshl_add_u32 v137, s61, 8, v136
	v_or_b32_e32 v160, s36, v138
	v_ashrrev_i32_e32 v161, 31, v160
	v_mad_i64_i32 v[162:163], s[12:13], s59, v137, 0
	v_lshl_add_u64 v[164:165], v[162:163], 1, s[42:43]
	v_lshlrev_b64 v[162:163], 1, v[160:161]
	v_lshl_add_u64 v[168:169], v[164:165], 0, v[162:163]
	v_cvt_pk_bf16_f32 v164, v124, v125
	v_cvt_pk_bf16_f32 v165, v126, v127
	v_cvt_pk_bf16_f32 v166, v120, v121
	v_cvt_pk_bf16_f32 v167, v122, v123
	global_store_dwordx4 v[168:169], v[164:167], off
	v_or_b32_e32 v144, 16, v137
	s_cmp_lt_i32 s61, 16
	v_cvt_pk_bf16_f32 v164, v116, v117
	v_cvt_pk_bf16_f32 v165, v118, v119
	v_cvt_pk_bf16_f32 v166, v100, v101
	v_cvt_pk_bf16_f32 v167, v102, v103
	global_store_dwordx4 v[168:169], v[164:167], off offset:256
	s_nop 1
	v_mad_i64_i32 v[164:165], s[12:13], s59, v144, 0
	v_lshl_add_u64 v[164:165], v[164:165], 1, s[42:43]
	v_lshl_add_u64 v[168:169], v[164:165], 0, v[162:163]
	v_cvt_pk_bf16_f32 v164, v112, v113
	v_cvt_pk_bf16_f32 v165, v114, v115
	v_cvt_pk_bf16_f32 v166, v108, v109
	v_cvt_pk_bf16_f32 v167, v110, v111
	global_store_dwordx4 v[168:169], v[164:167], off
	v_or_b32_e32 v144, 32, v137
	s_nop 0
	v_cvt_pk_bf16_f32 v164, v92, v93
	v_cvt_pk_bf16_f32 v165, v94, v95
	v_cvt_pk_bf16_f32 v166, v84, v85
	v_cvt_pk_bf16_f32 v167, v86, v87
	global_store_dwordx4 v[168:169], v[164:167], off offset:256
	s_nop 1
	v_mad_i64_i32 v[164:165], s[12:13], s59, v144, 0
	v_lshl_add_u64 v[164:165], v[164:165], 1, s[42:43]
	v_lshl_add_u64 v[168:169], v[164:165], 0, v[162:163]
	v_cvt_pk_bf16_f32 v164, v104, v105
	v_cvt_pk_bf16_f32 v165, v106, v107
	v_cvt_pk_bf16_f32 v166, v96, v97
	v_cvt_pk_bf16_f32 v167, v98, v99
	global_store_dwordx4 v[168:169], v[164:167], off
	v_or_b32_e32 v144, 48, v137
	s_nop 0
	v_cvt_pk_bf16_f32 v164, v76, v77
	v_cvt_pk_bf16_f32 v165, v78, v79
	v_cvt_pk_bf16_f32 v166, v72, v73
	v_cvt_pk_bf16_f32 v167, v74, v75
	global_store_dwordx4 v[168:169], v[164:167], off offset:256
	s_nop 1
	v_mad_i64_i32 v[164:165], s[12:13], s59, v144, 0
	v_lshl_add_u64 v[164:165], v[164:165], 1, s[42:43]
	v_lshl_add_u64 v[168:169], v[164:165], 0, v[162:163]
	v_cvt_pk_bf16_f32 v164, v88, v89
	v_cvt_pk_bf16_f32 v165, v90, v91
	v_cvt_pk_bf16_f32 v166, v80, v81
	v_cvt_pk_bf16_f32 v167, v82, v83
	global_store_dwordx4 v[168:169], v[164:167], off
	v_add_u32_e32 v144, 0x80, v137
	s_nop 0
	v_cvt_pk_bf16_f32 v164, v68, v69
	v_cvt_pk_bf16_f32 v165, v70, v71
	v_cvt_pk_bf16_f32 v166, v64, v65
	v_cvt_pk_bf16_f32 v167, v66, v67
	global_store_dwordx4 v[168:169], v[164:167], off offset:256
	s_nop 1
	v_mad_i64_i32 v[164:165], s[12:13], s59, v144, 0
	v_lshl_add_u64 v[164:165], v[164:165], 1, s[42:43]
	v_lshl_add_u64 v[168:169], v[164:165], 0, v[162:163]
	v_cvt_pk_bf16_f32 v164, v60, v61
	v_cvt_pk_bf16_f32 v165, v62, v63
	v_cvt_pk_bf16_f32 v166, v56, v57
	v_cvt_pk_bf16_f32 v167, v58, v59
	global_store_dwordx4 v[168:169], v[164:167], off
	v_add_u32_e32 v144, 0x90, v137
	s_nop 0
	v_cvt_pk_bf16_f32 v164, v44, v45
	v_cvt_pk_bf16_f32 v165, v46, v47
	v_cvt_pk_bf16_f32 v166, v32, v33
	v_cvt_pk_bf16_f32 v167, v34, v35
	global_store_dwordx4 v[168:169], v[164:167], off offset:256
	s_nop 1
	v_mad_i64_i32 v[164:165], s[12:13], s59, v144, 0
	v_lshl_add_u64 v[164:165], v[164:165], 1, s[42:43]
	v_lshl_add_u64 v[168:169], v[164:165], 0, v[162:163]
	v_cvt_pk_bf16_f32 v164, v52, v53
	v_cvt_pk_bf16_f32 v165, v54, v55
	v_cvt_pk_bf16_f32 v166, v48, v49
	v_cvt_pk_bf16_f32 v167, v50, v51
	global_store_dwordx4 v[168:169], v[164:167], off
	v_add_u32_e32 v144, 0xa0, v137
	v_add_u32_e32 v137, 0xb0, v137
	v_cvt_pk_bf16_f32 v164, v28, v29
	v_cvt_pk_bf16_f32 v165, v30, v31
	v_cvt_pk_bf16_f32 v166, v16, v17
	v_cvt_pk_bf16_f32 v167, v18, v19
	global_store_dwordx4 v[168:169], v[164:167], off offset:256
	s_nop 1
	v_mad_i64_i32 v[164:165], s[12:13], s59, v144, 0
	v_lshl_add_u64 v[164:165], v[164:165], 1, s[42:43]
	v_lshl_add_u64 v[168:169], v[164:165], 0, v[162:163]
	v_cvt_pk_bf16_f32 v164, v40, v41
	v_cvt_pk_bf16_f32 v165, v42, v43
	v_cvt_pk_bf16_f32 v166, v36, v37
	v_cvt_pk_bf16_f32 v167, v38, v39
	global_store_dwordx4 v[168:169], v[164:167], off
	s_nop 1
	v_cvt_pk_bf16_f32 v164, v12, v13
	v_cvt_pk_bf16_f32 v165, v14, v15
	v_cvt_pk_bf16_f32 v166, v8, v9
	v_cvt_pk_bf16_f32 v167, v10, v11
	global_store_dwordx4 v[168:169], v[164:167], off offset:256
	s_nop 1
	v_mad_i64_i32 v[164:165], s[12:13], s59, v137, 0
	s_cselect_b64 s[12:13], -1, 0
	v_lshl_add_u64 v[164:165], v[164:165], 1, s[42:43]
	s_and_b64 s[12:13], s[8:9], s[12:13]
	v_lshl_add_u64 v[166:167], v[164:165], 0, v[162:163]
	v_cvt_pk_bf16_f32 v162, v24, v25
	v_cvt_pk_bf16_f32 v163, v26, v27
	v_cvt_pk_bf16_f32 v164, v20, v21
	v_cvt_pk_bf16_f32 v165, v22, v23
	s_andn2_b64 vcc, exec, s[12:13]
	global_store_dwordx4 v[166:167], v[162:165], off
	s_nop 1
	v_cvt_pk_bf16_f32 v162, v4, v5
	v_cvt_pk_bf16_f32 v163, v6, v7
	v_cvt_pk_bf16_f32 v164, v0, v1
	v_cvt_pk_bf16_f32 v165, v2, v3
	global_store_dwordx4 v[166:167], v[162:165], off offset:256
	s_cbranch_vccnz .LBB0_380
	s_cmp_lt_i32 s80, 5
	s_cbranch_scc1 .LBB0_394
	s_cmp_eq_u32 s80, 5
	s_mov_b64 s[14:15], -1
	s_cbranch_scc0 .LBB0_393
	s_mov_b64 s[14:15], 0
